# v24 + hand-written FFN edge fix-up phase (all loads of an item issued together, two batches)
# speedup vs baseline: 1.0001x; 1.0001x over previous
; __device__ __forceinline__ float gelu_tanh(float x) { const float z = x * ((x * x) * (-0.10294324f) + (-2.3022082f)); return x * __builtin_amdgcn_rcpf(1.f + __builtin_amdgcn_exp2f(z)); }
; __device__ void phase_ffn_fix(PP P, int wid, int layer) {
;     ...
;     for (int it = blockIdx.x * NTHREADS + tidx; it < NQ * 2 * 352; it += gridDim.x * NTHREADS) {
;         const int c8 = (it % 352) * 8, qs = it / 352, q = qs >> 1, sd = qs & 1;
;         const int row = q * 64 + (sd ? 63 : 0), l = row & (SEQL - 1);
;         const int cg = c8 >> 3;
;         const bf16_t* me = eb + ((size_t)((q * 2 + sd) * 352 + cg) * 4) * 8;
;         float pa[8], pv[8];
;         unpack8(*(const u32x4*)(me + 16), pa); unpack8(*(const u32x4*)(me + 24), pv);
;         const bool has_nb = sd ? (l < SEQL - 1) : (l > 0);
;         if (has_nb) {
;             const bf16_t* nb = eb + ((size_t)(((sd ? q + 1 : q - 1) * 2 + (sd ? 0 : 1)) * 352 + cg) * 4) * 8;
;             float ra[8], rv[8], wa[8], wv[8];
;             unpack8(*(const u32x4*)(nb), ra); unpack8(*(const u32x4*)(nb + 8), rv);
;             load8f(cw + (sd ? 2 : 0) * F2 + c8, wa); load8f(cw + (sd ? 2 : 0) * F2 + F + c8, wv);
; #pragma unroll
;             for (int e = 0; e < 8; ++e) { pa[e] += wa[e] * ra[e]; pv[e] += wv[e] * rv[e]; }
;         }
;         float o[8];
; #pragma unroll
;         for (int e = 0; e < 8; ++e) o[e] = gelu_tanh(pa[e]) * pv[e];
;         *(u32x4*)(G + (size_t)row * F + c8) = pack8(o);
;     }
.LBB0_214:
	s_cmp_lt_i32 s44, 3
	s_cbranch_scc1 .LBB0_238
	s_cmp_lg_u32 s44, 3
	s_cbranch_scc0 .LBB0_222
	v_mbcnt_lo_u32_b32 v0, -1, 0
	v_mbcnt_hi_u32_b32 v0, -1, v0
	s_load_dwordx2 s[10:11], s[58:59], 0xc0
	v_readlane_b32 s30, v255, 15
	s_add_u32 s68, s22, 0x18660000
	s_addc_u32 s69, s23, 0
	s_mov_b32 s55, 0xffff0000
	v_mov_b32_e32 v8, 0xbdd2d3e8
	v_mov_b32_e32 v9, 0xbdd2d3e8
	v_mov_b32_e32 v10, 0xc0135761
	v_mov_b32_e32 v11, 0xc0135761
	s_mul_i32 s4, s25, 0x10800
	s_waitcnt lgkmcnt(0)
	s_add_u32 s10, s10, s4
	s_addc_u32 s11, s11, 0
	s_add_u32 s72, s10, 0x2c00
	s_addc_u32 s73, s11, 0
	v_add_u32_e32 v1, s30, v0
	v_lshrrev_b32_e32 v4, 5, v1
	v_mul_u32_u24_e32 v4, 0xba2f, v4
	v_lshrrev_b32_e32 v2, 19, v4
	v_mul_u32_u24_e32 v4, 0x160, v2
	v_sub_u32_e32 v3, v1, v4
	v_and_b32_e32 v5, 1, v2
	v_lshrrev_b32_e32 v6, 1, v2
	v_lshlrev_b32_e32 v12, 6, v1
	v_and_b32_e32 v7, 31, v6
	v_mul_u32_u24_e32 v4, 31, v5
	v_cmp_ne_u32_e32 vcc, v7, v4
	v_lshlrev_b32_e32 v4, 1, v5
	v_subrev_u32_e32 v4, 1, v4
	v_mul_i32_i24_e32 v4, 0x5800, v4
	v_add_u32_e32 v13, v12, v4
	v_cndmask_b32_e32 v13, v12, v13, vcc
	v_cndmask_b32_e64 v18, 0, 1.0, vcc
	v_cndmask_b32_e64 v19, 0, 1.0, vcc
	v_mul_u32_u24_e32 v14, 0xb000, v5
	v_lshl_add_u32 v14, v3, 5, v14
	v_lshlrev_b32_e32 v4, 6, v6
	v_mad_u32_u24 v4, v5, 63, v4
	v_mul_lo_u32 v4, v4, s78
	v_lshl_add_u32 v16, v3, 4, v4
	global_load_dwordx4 v[32:35], v12, s[68:69] offset:32
	global_load_dwordx4 v[36:39], v12, s[68:69] offset:48
	global_load_dwordx4 v[40:43], v13, s[68:69]
	global_load_dwordx4 v[44:47], v13, s[68:69] offset:16
	global_load_dwordx4 v[48:51], v14, s[10:11]
	global_load_dwordx4 v[52:55], v14, s[10:11] offset:16
	global_load_dwordx4 v[56:59], v14, s[72:73]
	global_load_dwordx4 v[60:63], v14, s[72:73] offset:16
	s_add_i32 s30, s30, s76
	v_add_u32_e32 v1, s30, v0
	v_lshrrev_b32_e32 v4, 5, v1
	v_mul_u32_u24_e32 v4, 0xba2f, v4
	v_lshrrev_b32_e32 v2, 19, v4
	v_mul_u32_u24_e32 v4, 0x160, v2
	v_sub_u32_e32 v3, v1, v4
	v_and_b32_e32 v5, 1, v2
	v_lshrrev_b32_e32 v6, 1, v2
	v_lshlrev_b32_e32 v12, 6, v1
	v_and_b32_e32 v7, 31, v6
	v_mul_u32_u24_e32 v4, 31, v5
	v_cmp_ne_u32_e32 vcc, v7, v4
	v_lshlrev_b32_e32 v4, 1, v5
	v_subrev_u32_e32 v4, 1, v4
	v_mul_i32_i24_e32 v4, 0x5800, v4
	v_add_u32_e32 v13, v12, v4
	v_cndmask_b32_e32 v13, v12, v13, vcc
	v_cndmask_b32_e64 v22, 0, 1.0, vcc
	v_cndmask_b32_e64 v23, 0, 1.0, vcc
	v_mul_u32_u24_e32 v14, 0xb000, v5
	v_lshl_add_u32 v14, v3, 5, v14
	v_lshlrev_b32_e32 v4, 6, v6
	v_mad_u32_u24 v4, v5, 63, v4
	v_mul_lo_u32 v4, v4, s78
	v_lshl_add_u32 v20, v3, 4, v4
	global_load_dwordx4 v[64:67], v12, s[68:69] offset:32
	global_load_dwordx4 v[68:71], v12, s[68:69] offset:48
	global_load_dwordx4 v[72:75], v13, s[68:69]
	global_load_dwordx4 v[76:79], v13, s[68:69] offset:16
	global_load_dwordx4 v[80:83], v14, s[10:11]
	global_load_dwordx4 v[84:87], v14, s[10:11] offset:16
	global_load_dwordx4 v[88:91], v14, s[72:73]
	global_load_dwordx4 v[92:95], v14, s[72:73] offset:16
	s_add_i32 s30, s30, s76
	v_add_u32_e32 v1, s30, v0
	v_lshrrev_b32_e32 v4, 5, v1
	v_mul_u32_u24_e32 v4, 0xba2f, v4
	v_lshrrev_b32_e32 v2, 19, v4
	v_mul_u32_u24_e32 v4, 0x160, v2
	v_sub_u32_e32 v3, v1, v4
	v_and_b32_e32 v5, 1, v2
	v_lshrrev_b32_e32 v6, 1, v2
	v_lshlrev_b32_e32 v12, 6, v1
	v_and_b32_e32 v7, 31, v6
	v_mul_u32_u24_e32 v4, 31, v5
	v_cmp_ne_u32_e32 vcc, v7, v4
	v_lshlrev_b32_e32 v4, 1, v5
	v_subrev_u32_e32 v4, 1, v4
	v_mul_i32_i24_e32 v4, 0x5800, v4
	v_add_u32_e32 v13, v12, v4
	v_cndmask_b32_e32 v13, v12, v13, vcc
	v_cndmask_b32_e64 v26, 0, 1.0, vcc
	v_cndmask_b32_e64 v27, 0, 1.0, vcc
	v_mul_u32_u24_e32 v14, 0xb000, v5
	v_lshl_add_u32 v14, v3, 5, v14
	v_lshlrev_b32_e32 v4, 6, v6
	v_mad_u32_u24 v4, v5, 63, v4
	v_mul_lo_u32 v4, v4, s78
	v_lshl_add_u32 v24, v3, 4, v4
	global_load_dwordx4 v[96:99], v12, s[68:69] offset:32
	global_load_dwordx4 v[100:103], v12, s[68:69] offset:48
	global_load_dwordx4 v[104:107], v13, s[68:69]
	global_load_dwordx4 v[108:111], v13, s[68:69] offset:16
	global_load_dwordx4 v[112:115], v14, s[10:11]
	global_load_dwordx4 v[116:119], v14, s[10:11] offset:16
	global_load_dwordx4 v[120:123], v14, s[72:73]
	global_load_dwordx4 v[124:127], v14, s[72:73] offset:16
	s_add_i32 s30, s30, s76
	s_waitcnt vmcnt(0)
	v_lshlrev_b32_e32 v128, 16, v40
	v_and_b32_e32 v129, s55, v40
	v_lshlrev_b32_e32 v130, 16, v41
	v_and_b32_e32 v131, s55, v41
	v_lshlrev_b32_e32 v132, 16, v42
	v_and_b32_e32 v133, s55, v42
	v_lshlrev_b32_e32 v134, 16, v43
	v_and_b32_e32 v135, s55, v43
	v_lshlrev_b32_e32 v136, 16, v44
	v_and_b32_e32 v137, s55, v44
	v_lshlrev_b32_e32 v138, 16, v45
	v_and_b32_e32 v139, s55, v45
	v_lshlrev_b32_e32 v140, 16, v46
	v_and_b32_e32 v141, s55, v46
	v_lshlrev_b32_e32 v142, 16, v47
	v_and_b32_e32 v143, s55, v47
	v_pk_mul_f32 v[128:129], v[128:129], v[18:19]
	v_pk_mul_f32 v[130:131], v[130:131], v[18:19]
	v_pk_mul_f32 v[132:133], v[132:133], v[18:19]
	v_pk_mul_f32 v[134:135], v[134:135], v[18:19]
	v_pk_mul_f32 v[136:137], v[136:137], v[18:19]
	v_pk_mul_f32 v[138:139], v[138:139], v[18:19]
	v_pk_mul_f32 v[140:141], v[140:141], v[18:19]
	v_pk_mul_f32 v[142:143], v[142:143], v[18:19]
	v_lshlrev_b32_e32 v144, 16, v32
	v_and_b32_e32 v145, s55, v32
	v_lshlrev_b32_e32 v146, 16, v33
	v_and_b32_e32 v147, s55, v33
	v_lshlrev_b32_e32 v148, 16, v34
	v_and_b32_e32 v149, s55, v34
	v_lshlrev_b32_e32 v150, 16, v35
	v_and_b32_e32 v151, s55, v35
	v_lshlrev_b32_e32 v152, 16, v36
	v_and_b32_e32 v153, s55, v36
	v_lshlrev_b32_e32 v154, 16, v37
	v_and_b32_e32 v155, s55, v37
	v_lshlrev_b32_e32 v156, 16, v38
	v_and_b32_e32 v157, s55, v38
	v_lshlrev_b32_e32 v158, 16, v39
	v_and_b32_e32 v159, s55, v39
	v_pk_fma_f32 v[144:145], v[48:49], v[128:129], v[144:145]
; __device__ __forceinline__ float gelu_tanh(float x) { const float z = x * ((x * x) * (-0.10294324f) + (-2.3022082f)); return x * __builtin_amdgcn_rcpf(1.f + __builtin_amdgcn_exp2f(z)); }
; __device__ void phase_ffn_fix(PP P, int wid, int layer) {
;     ...
;     for (int it = blockIdx.x * NTHREADS + tidx; it < NQ * 2 * 352; it += gridDim.x * NTHREADS) {
;         const int c8 = (it % 352) * 8, qs = it / 352, q = qs >> 1, sd = qs & 1;
;         const int row = q * 64 + (sd ? 63 : 0), l = row & (SEQL - 1);
;         const int cg = c8 >> 3;
;         const bf16_t* me = eb + ((size_t)((q * 2 + sd) * 352 + cg) * 4) * 8;
;         float pa[8], pv[8];
;         unpack8(*(const u32x4*)(me + 16), pa); unpack8(*(const u32x4*)(me + 24), pv);
;         const bool has_nb = sd ? (l < SEQL - 1) : (l > 0);
;         if (has_nb) {
;             const bf16_t* nb = eb + ((size_t)(((sd ? q + 1 : q - 1) * 2 + (sd ? 0 : 1)) * 352 + cg) * 4) * 8;
;             float ra[8], rv[8], wa[8], wv[8];
;             unpack8(*(const u32x4*)(nb), ra); unpack8(*(const u32x4*)(nb + 8), rv);
;             load8f(cw + (sd ? 2 : 0) * F2 + c8, wa); load8f(cw + (sd ? 2 : 0) * F2 + F + c8, wv);
; #pragma unroll
;             for (int e = 0; e < 8; ++e) { pa[e] += wa[e] * ra[e]; pv[e] += wv[e] * rv[e]; }
;         }
;         float o[8];
; #pragma unroll
;         for (int e = 0; e < 8; ++e) o[e] = gelu_tanh(pa[e]) * pv[e];
;         *(u32x4*)(G + (size_t)row * F + c8) = pack8(o);
;     }
	v_pk_fma_f32 v[146:147], v[50:51], v[130:131], v[146:147]
	v_pk_fma_f32 v[148:149], v[52:53], v[132:133], v[148:149]
	v_pk_fma_f32 v[150:151], v[54:55], v[134:135], v[150:151]
	v_pk_fma_f32 v[152:153], v[56:57], v[136:137], v[152:153]
	v_pk_fma_f32 v[154:155], v[58:59], v[138:139], v[154:155]
	v_pk_fma_f32 v[156:157], v[60:61], v[140:141], v[156:157]
	v_pk_fma_f32 v[158:159], v[62:63], v[142:143], v[158:159]
	v_pk_mul_f32 v[128:129], v[144:145], v[144:145]
	v_pk_mul_f32 v[130:131], v[146:147], v[146:147]
	v_pk_mul_f32 v[132:133], v[148:149], v[148:149]
	v_pk_mul_f32 v[134:135], v[150:151], v[150:151]
	v_pk_fma_f32 v[128:129], v[128:129], v[8:9], v[10:11]
	v_pk_fma_f32 v[130:131], v[130:131], v[8:9], v[10:11]
	v_pk_fma_f32 v[132:133], v[132:133], v[8:9], v[10:11]
	v_pk_fma_f32 v[134:135], v[134:135], v[8:9], v[10:11]
	v_pk_mul_f32 v[128:129], v[144:145], v[128:129]
	v_pk_mul_f32 v[130:131], v[146:147], v[130:131]
	v_pk_mul_f32 v[132:133], v[148:149], v[132:133]
	v_pk_mul_f32 v[134:135], v[150:151], v[134:135]
	v_exp_f32_e32 v128, v128
	v_exp_f32_e32 v129, v129
	v_exp_f32_e32 v130, v130
	v_exp_f32_e32 v131, v131
	v_exp_f32_e32 v132, v132
	v_exp_f32_e32 v133, v133
	v_exp_f32_e32 v134, v134
	v_exp_f32_e32 v135, v135
	s_nop 0
	v_pk_add_f32 v[128:129], v[128:129], 1.0 op_sel_hi:[1,0]
	v_pk_add_f32 v[130:131], v[130:131], 1.0 op_sel_hi:[1,0]
	v_pk_add_f32 v[132:133], v[132:133], 1.0 op_sel_hi:[1,0]
	v_pk_add_f32 v[134:135], v[134:135], 1.0 op_sel_hi:[1,0]
	v_rcp_f32_e32 v128, v128
	v_rcp_f32_e32 v129, v129
	v_rcp_f32_e32 v130, v130
	v_rcp_f32_e32 v131, v131
	v_rcp_f32_e32 v132, v132
	v_rcp_f32_e32 v133, v133
	v_rcp_f32_e32 v134, v134
	v_rcp_f32_e32 v135, v135
	s_nop 0
	v_pk_mul_f32 v[144:145], v[144:145], v[128:129]
	v_pk_mul_f32 v[146:147], v[146:147], v[130:131]
	v_pk_mul_f32 v[148:149], v[148:149], v[132:133]
	v_pk_mul_f32 v[150:151], v[150:151], v[134:135]
	v_pk_mul_f32 v[144:145], v[144:145], v[152:153]
	v_pk_mul_f32 v[146:147], v[146:147], v[154:155]
	v_pk_mul_f32 v[148:149], v[148:149], v[156:157]
	v_pk_mul_f32 v[150:151], v[150:151], v[158:159]
	v_cvt_pk_bf16_f32 v136, v144, v145
	v_cvt_pk_bf16_f32 v137, v146, v147
	v_cvt_pk_bf16_f32 v138, v148, v149
	v_cvt_pk_bf16_f32 v139, v150, v151
	global_store_dwordx4 v16, v[136:139], s[56:57]
	v_lshlrev_b32_e32 v128, 16, v72
	v_and_b32_e32 v129, s55, v72
	v_lshlrev_b32_e32 v130, 16, v73
	v_and_b32_e32 v131, s55, v73
	v_lshlrev_b32_e32 v132, 16, v74
	v_and_b32_e32 v133, s55, v74
	v_lshlrev_b32_e32 v134, 16, v75
	v_and_b32_e32 v135, s55, v75
	v_lshlrev_b32_e32 v136, 16, v76
	v_and_b32_e32 v137, s55, v76
	v_lshlrev_b32_e32 v138, 16, v77
	v_and_b32_e32 v139, s55, v77
	v_lshlrev_b32_e32 v140, 16, v78
	v_and_b32_e32 v141, s55, v78
	v_lshlrev_b32_e32 v142, 16, v79
	v_and_b32_e32 v143, s55, v79
	v_pk_mul_f32 v[128:129], v[128:129], v[22:23]
	v_pk_mul_f32 v[130:131], v[130:131], v[22:23]
	v_pk_mul_f32 v[132:133], v[132:133], v[22:23]
	v_pk_mul_f32 v[134:135], v[134:135], v[22:23]
	v_pk_mul_f32 v[136:137], v[136:137], v[22:23]
	v_pk_mul_f32 v[138:139], v[138:139], v[22:23]
	v_pk_mul_f32 v[140:141], v[140:141], v[22:23]
	v_pk_mul_f32 v[142:143], v[142:143], v[22:23]
	v_lshlrev_b32_e32 v144, 16, v64
	v_and_b32_e32 v145, s55, v64
	v_lshlrev_b32_e32 v146, 16, v65
	v_and_b32_e32 v147, s55, v65
	v_lshlrev_b32_e32 v148, 16, v66
	v_and_b32_e32 v149, s55, v66
	v_lshlrev_b32_e32 v150, 16, v67
	v_and_b32_e32 v151, s55, v67
	v_lshlrev_b32_e32 v152, 16, v68
	v_and_b32_e32 v153, s55, v68
	v_lshlrev_b32_e32 v154, 16, v69
	v_and_b32_e32 v155, s55, v69
	v_lshlrev_b32_e32 v156, 16, v70
	v_and_b32_e32 v157, s55, v70
	v_lshlrev_b32_e32 v158, 16, v71
	v_and_b32_e32 v159, s55, v71
	v_pk_fma_f32 v[144:145], v[80:81], v[128:129], v[144:145]
	v_pk_fma_f32 v[146:147], v[82:83], v[130:131], v[146:147]
	v_pk_fma_f32 v[148:149], v[84:85], v[132:133], v[148:149]
	v_pk_fma_f32 v[150:151], v[86:87], v[134:135], v[150:151]
	v_pk_fma_f32 v[152:153], v[88:89], v[136:137], v[152:153]
	v_pk_fma_f32 v[154:155], v[90:91], v[138:139], v[154:155]
	v_pk_fma_f32 v[156:157], v[92:93], v[140:141], v[156:157]
	v_pk_fma_f32 v[158:159], v[94:95], v[142:143], v[158:159]
	v_pk_mul_f32 v[128:129], v[144:145], v[144:145]
	v_pk_mul_f32 v[130:131], v[146:147], v[146:147]
	v_pk_mul_f32 v[132:133], v[148:149], v[148:149]
	v_pk_mul_f32 v[134:135], v[150:151], v[150:151]
	v_pk_fma_f32 v[128:129], v[128:129], v[8:9], v[10:11]
	v_pk_fma_f32 v[130:131], v[130:131], v[8:9], v[10:11]
	v_pk_fma_f32 v[132:133], v[132:133], v[8:9], v[10:11]
	v_pk_fma_f32 v[134:135], v[134:135], v[8:9], v[10:11]
	v_pk_mul_f32 v[128:129], v[144:145], v[128:129]
	v_pk_mul_f32 v[130:131], v[146:147], v[130:131]
	v_pk_mul_f32 v[132:133], v[148:149], v[132:133]
	v_pk_mul_f32 v[134:135], v[150:151], v[134:135]
	v_exp_f32_e32 v128, v128
	v_exp_f32_e32 v129, v129
	v_exp_f32_e32 v130, v130
	v_exp_f32_e32 v131, v131
	v_exp_f32_e32 v132, v132
	v_exp_f32_e32 v133, v133
	v_exp_f32_e32 v134, v134
	v_exp_f32_e32 v135, v135
	s_nop 0
	v_pk_add_f32 v[128:129], v[128:129], 1.0 op_sel_hi:[1,0]
	v_pk_add_f32 v[130:131], v[130:131], 1.0 op_sel_hi:[1,0]
	v_pk_add_f32 v[132:133], v[132:133], 1.0 op_sel_hi:[1,0]
	v_pk_add_f32 v[134:135], v[134:135], 1.0 op_sel_hi:[1,0]
	v_rcp_f32_e32 v128, v128
	v_rcp_f32_e32 v129, v129
	v_rcp_f32_e32 v130, v130
	v_rcp_f32_e32 v131, v131
	v_rcp_f32_e32 v132, v132
	v_rcp_f32_e32 v133, v133
	v_rcp_f32_e32 v134, v134
	v_rcp_f32_e32 v135, v135
	s_nop 0
	v_pk_mul_f32 v[144:145], v[144:145], v[128:129]
	v_pk_mul_f32 v[146:147], v[146:147], v[130:131]
	v_pk_mul_f32 v[148:149], v[148:149], v[132:133]
	v_pk_mul_f32 v[150:151], v[150:151], v[134:135]
	v_pk_mul_f32 v[144:145], v[144:145], v[152:153]
; __device__ __forceinline__ float gelu_tanh(float x) { const float z = x * ((x * x) * (-0.10294324f) + (-2.3022082f)); return x * __builtin_amdgcn_rcpf(1.f + __builtin_amdgcn_exp2f(z)); }
; __device__ void phase_ffn_fix(PP P, int wid, int layer) {
;     ...
;     for (int it = blockIdx.x * NTHREADS + tidx; it < NQ * 2 * 352; it += gridDim.x * NTHREADS) {
;         const int c8 = (it % 352) * 8, qs = it / 352, q = qs >> 1, sd = qs & 1;
;         const int row = q * 64 + (sd ? 63 : 0), l = row & (SEQL - 1);
;         const int cg = c8 >> 3;
;         const bf16_t* me = eb + ((size_t)((q * 2 + sd) * 352 + cg) * 4) * 8;
;         float pa[8], pv[8];
;         unpack8(*(const u32x4*)(me + 16), pa); unpack8(*(const u32x4*)(me + 24), pv);
;         const bool has_nb = sd ? (l < SEQL - 1) : (l > 0);
;         if (has_nb) {
;             const bf16_t* nb = eb + ((size_t)(((sd ? q + 1 : q - 1) * 2 + (sd ? 0 : 1)) * 352 + cg) * 4) * 8;
;             float ra[8], rv[8], wa[8], wv[8];
;             unpack8(*(const u32x4*)(nb), ra); unpack8(*(const u32x4*)(nb + 8), rv);
;             load8f(cw + (sd ? 2 : 0) * F2 + c8, wa); load8f(cw + (sd ? 2 : 0) * F2 + F + c8, wv);
; #pragma unroll
;             for (int e = 0; e < 8; ++e) { pa[e] += wa[e] * ra[e]; pv[e] += wv[e] * rv[e]; }
;         }
;         float o[8];
; #pragma unroll
;         for (int e = 0; e < 8; ++e) o[e] = gelu_tanh(pa[e]) * pv[e];
;         *(u32x4*)(G + (size_t)row * F + c8) = pack8(o);
;     }
	v_pk_mul_f32 v[146:147], v[146:147], v[154:155]
	v_pk_mul_f32 v[148:149], v[148:149], v[156:157]
	v_pk_mul_f32 v[150:151], v[150:151], v[158:159]
	v_cvt_pk_bf16_f32 v136, v144, v145
	v_cvt_pk_bf16_f32 v137, v146, v147
	v_cvt_pk_bf16_f32 v138, v148, v149
	v_cvt_pk_bf16_f32 v139, v150, v151
	global_store_dwordx4 v20, v[136:139], s[56:57]
	v_lshlrev_b32_e32 v128, 16, v104
	v_and_b32_e32 v129, s55, v104
	v_lshlrev_b32_e32 v130, 16, v105
	v_and_b32_e32 v131, s55, v105
	v_lshlrev_b32_e32 v132, 16, v106
	v_and_b32_e32 v133, s55, v106
	v_lshlrev_b32_e32 v134, 16, v107
	v_and_b32_e32 v135, s55, v107
	v_lshlrev_b32_e32 v136, 16, v108
	v_and_b32_e32 v137, s55, v108
	v_lshlrev_b32_e32 v138, 16, v109
	v_and_b32_e32 v139, s55, v109
	v_lshlrev_b32_e32 v140, 16, v110
	v_and_b32_e32 v141, s55, v110
	v_lshlrev_b32_e32 v142, 16, v111
	v_and_b32_e32 v143, s55, v111
	v_pk_mul_f32 v[128:129], v[128:129], v[26:27]
	v_pk_mul_f32 v[130:131], v[130:131], v[26:27]
	v_pk_mul_f32 v[132:133], v[132:133], v[26:27]
	v_pk_mul_f32 v[134:135], v[134:135], v[26:27]
	v_pk_mul_f32 v[136:137], v[136:137], v[26:27]
	v_pk_mul_f32 v[138:139], v[138:139], v[26:27]
	v_pk_mul_f32 v[140:141], v[140:141], v[26:27]
	v_pk_mul_f32 v[142:143], v[142:143], v[26:27]
	v_lshlrev_b32_e32 v144, 16, v96
	v_and_b32_e32 v145, s55, v96
	v_lshlrev_b32_e32 v146, 16, v97
	v_and_b32_e32 v147, s55, v97
	v_lshlrev_b32_e32 v148, 16, v98
	v_and_b32_e32 v149, s55, v98
	v_lshlrev_b32_e32 v150, 16, v99
	v_and_b32_e32 v151, s55, v99
	v_lshlrev_b32_e32 v152, 16, v100
	v_and_b32_e32 v153, s55, v100
	v_lshlrev_b32_e32 v154, 16, v101
	v_and_b32_e32 v155, s55, v101
	v_lshlrev_b32_e32 v156, 16, v102
	v_and_b32_e32 v157, s55, v102
	v_lshlrev_b32_e32 v158, 16, v103
	v_and_b32_e32 v159, s55, v103
	v_pk_fma_f32 v[144:145], v[112:113], v[128:129], v[144:145]
	v_pk_fma_f32 v[146:147], v[114:115], v[130:131], v[146:147]
	v_pk_fma_f32 v[148:149], v[116:117], v[132:133], v[148:149]
	v_pk_fma_f32 v[150:151], v[118:119], v[134:135], v[150:151]
	v_pk_fma_f32 v[152:153], v[120:121], v[136:137], v[152:153]
	v_pk_fma_f32 v[154:155], v[122:123], v[138:139], v[154:155]
	v_pk_fma_f32 v[156:157], v[124:125], v[140:141], v[156:157]
	v_pk_fma_f32 v[158:159], v[126:127], v[142:143], v[158:159]
	v_pk_mul_f32 v[128:129], v[144:145], v[144:145]
	v_pk_mul_f32 v[130:131], v[146:147], v[146:147]
	v_pk_mul_f32 v[132:133], v[148:149], v[148:149]
	v_pk_mul_f32 v[134:135], v[150:151], v[150:151]
	v_pk_fma_f32 v[128:129], v[128:129], v[8:9], v[10:11]
	v_pk_fma_f32 v[130:131], v[130:131], v[8:9], v[10:11]
	v_pk_fma_f32 v[132:133], v[132:133], v[8:9], v[10:11]
	v_pk_fma_f32 v[134:135], v[134:135], v[8:9], v[10:11]
	v_pk_mul_f32 v[128:129], v[144:145], v[128:129]
	v_pk_mul_f32 v[130:131], v[146:147], v[130:131]
	v_pk_mul_f32 v[132:133], v[148:149], v[132:133]
	v_pk_mul_f32 v[134:135], v[150:151], v[134:135]
	v_exp_f32_e32 v128, v128
	v_exp_f32_e32 v129, v129
	v_exp_f32_e32 v130, v130
	v_exp_f32_e32 v131, v131
	v_exp_f32_e32 v132, v132
	v_exp_f32_e32 v133, v133
	v_exp_f32_e32 v134, v134
	v_exp_f32_e32 v135, v135
	s_nop 0
	v_pk_add_f32 v[128:129], v[128:129], 1.0 op_sel_hi:[1,0]
	v_pk_add_f32 v[130:131], v[130:131], 1.0 op_sel_hi:[1,0]
	v_pk_add_f32 v[132:133], v[132:133], 1.0 op_sel_hi:[1,0]
	v_pk_add_f32 v[134:135], v[134:135], 1.0 op_sel_hi:[1,0]
	v_rcp_f32_e32 v128, v128
	v_rcp_f32_e32 v129, v129
	v_rcp_f32_e32 v130, v130
	v_rcp_f32_e32 v131, v131
	v_rcp_f32_e32 v132, v132
	v_rcp_f32_e32 v133, v133
	v_rcp_f32_e32 v134, v134
	v_rcp_f32_e32 v135, v135
	s_nop 0
	v_pk_mul_f32 v[144:145], v[144:145], v[128:129]
	v_pk_mul_f32 v[146:147], v[146:147], v[130:131]
	v_pk_mul_f32 v[148:149], v[148:149], v[132:133]
	v_pk_mul_f32 v[150:151], v[150:151], v[134:135]
	v_pk_mul_f32 v[144:145], v[144:145], v[152:153]
	v_pk_mul_f32 v[146:147], v[146:147], v[154:155]
	v_pk_mul_f32 v[148:149], v[148:149], v[156:157]
	v_pk_mul_f32 v[150:151], v[150:151], v[158:159]
	v_cvt_pk_bf16_f32 v136, v144, v145
	v_cvt_pk_bf16_f32 v137, v146, v147
	v_cvt_pk_bf16_f32 v138, v148, v149
	v_cvt_pk_bf16_f32 v139, v150, v151
	global_store_dwordx4 v24, v[136:139], s[56:57]
	v_add_u32_e32 v1, s30, v0
	v_lshrrev_b32_e32 v4, 5, v1
	v_mul_u32_u24_e32 v4, 0xba2f, v4
	v_lshrrev_b32_e32 v2, 19, v4
	v_mul_u32_u24_e32 v4, 0x160, v2
	v_sub_u32_e32 v3, v1, v4
	v_and_b32_e32 v5, 1, v2
	v_lshrrev_b32_e32 v6, 1, v2
	v_lshlrev_b32_e32 v12, 6, v1
	v_and_b32_e32 v7, 31, v6
	v_mul_u32_u24_e32 v4, 31, v5
	v_cmp_ne_u32_e32 vcc, v7, v4
	v_lshlrev_b32_e32 v4, 1, v5
	v_subrev_u32_e32 v4, 1, v4
	v_mul_i32_i24_e32 v4, 0x5800, v4
	v_add_u32_e32 v13, v12, v4
	v_cndmask_b32_e32 v13, v12, v13, vcc
	v_cndmask_b32_e64 v18, 0, 1.0, vcc
	v_cndmask_b32_e64 v19, 0, 1.0, vcc
	v_mul_u32_u24_e32 v14, 0xb000, v5
	v_lshl_add_u32 v14, v3, 5, v14
	v_lshlrev_b32_e32 v4, 6, v6
	v_mad_u32_u24 v4, v5, 63, v4
	v_mul_lo_u32 v4, v4, s78
	v_lshl_add_u32 v16, v3, 4, v4
	global_load_dwordx4 v[32:35], v12, s[68:69] offset:32
	global_load_dwordx4 v[36:39], v12, s[68:69] offset:48
	global_load_dwordx4 v[40:43], v13, s[68:69]
	global_load_dwordx4 v[44:47], v13, s[68:69] offset:16
	global_load_dwordx4 v[48:51], v14, s[10:11]
	global_load_dwordx4 v[52:55], v14, s[10:11] offset:16
	global_load_dwordx4 v[56:59], v14, s[72:73]
	global_load_dwordx4 v[60:63], v14, s[72:73] offset:16
	s_add_i32 s30, s30, s76
	v_add_u32_e32 v1, s30, v0
	v_lshrrev_b32_e32 v4, 5, v1
	v_mul_u32_u24_e32 v4, 0xba2f, v4
	v_lshrrev_b32_e32 v2, 19, v4
	v_mul_u32_u24_e32 v4, 0x160, v2
	v_sub_u32_e32 v3, v1, v4
	v_and_b32_e32 v5, 1, v2
	v_lshrrev_b32_e32 v6, 1, v2
	v_lshlrev_b32_e32 v12, 6, v1
	v_and_b32_e32 v7, 31, v6
	v_mul_u32_u24_e32 v4, 31, v5
	v_cmp_ne_u32_e32 vcc, v7, v4
; __device__ __forceinline__ float gelu_tanh(float x) { const float z = x * ((x * x) * (-0.10294324f) + (-2.3022082f)); return x * __builtin_amdgcn_rcpf(1.f + __builtin_amdgcn_exp2f(z)); }
; __device__ void phase_ffn_fix(PP P, int wid, int layer) {
;     ...
;     for (int it = blockIdx.x * NTHREADS + tidx; it < NQ * 2 * 352; it += gridDim.x * NTHREADS) {
;         const int c8 = (it % 352) * 8, qs = it / 352, q = qs >> 1, sd = qs & 1;
;         const int row = q * 64 + (sd ? 63 : 0), l = row & (SEQL - 1);
;         const int cg = c8 >> 3;
;         const bf16_t* me = eb + ((size_t)((q * 2 + sd) * 352 + cg) * 4) * 8;
;         float pa[8], pv[8];
;         unpack8(*(const u32x4*)(me + 16), pa); unpack8(*(const u32x4*)(me + 24), pv);
;         const bool has_nb = sd ? (l < SEQL - 1) : (l > 0);
;         if (has_nb) {
;             const bf16_t* nb = eb + ((size_t)(((sd ? q + 1 : q - 1) * 2 + (sd ? 0 : 1)) * 352 + cg) * 4) * 8;
;             float ra[8], rv[8], wa[8], wv[8];
;             unpack8(*(const u32x4*)(nb), ra); unpack8(*(const u32x4*)(nb + 8), rv);
;             load8f(cw + (sd ? 2 : 0) * F2 + c8, wa); load8f(cw + (sd ? 2 : 0) * F2 + F + c8, wv);
; #pragma unroll
;             for (int e = 0; e < 8; ++e) { pa[e] += wa[e] * ra[e]; pv[e] += wv[e] * rv[e]; }
;         }
;         float o[8];
; #pragma unroll
;         for (int e = 0; e < 8; ++e) o[e] = gelu_tanh(pa[e]) * pv[e];
;         *(u32x4*)(G + (size_t)row * F + c8) = pack8(o);
;     }
	v_lshlrev_b32_e32 v4, 1, v5
	v_subrev_u32_e32 v4, 1, v4
	v_mul_i32_i24_e32 v4, 0x5800, v4
	v_add_u32_e32 v13, v12, v4
	v_cndmask_b32_e32 v13, v12, v13, vcc
	v_cndmask_b32_e64 v22, 0, 1.0, vcc
	v_cndmask_b32_e64 v23, 0, 1.0, vcc
	v_mul_u32_u24_e32 v14, 0xb000, v5
	v_lshl_add_u32 v14, v3, 5, v14
	v_lshlrev_b32_e32 v4, 6, v6
	v_mad_u32_u24 v4, v5, 63, v4
	v_mul_lo_u32 v4, v4, s78
	v_lshl_add_u32 v20, v3, 4, v4
	global_load_dwordx4 v[64:67], v12, s[68:69] offset:32
	global_load_dwordx4 v[68:71], v12, s[68:69] offset:48
	global_load_dwordx4 v[72:75], v13, s[68:69]
	global_load_dwordx4 v[76:79], v13, s[68:69] offset:16
	global_load_dwordx4 v[80:83], v14, s[10:11]
	global_load_dwordx4 v[84:87], v14, s[10:11] offset:16
	global_load_dwordx4 v[88:91], v14, s[72:73]
	global_load_dwordx4 v[92:95], v14, s[72:73] offset:16
	s_add_i32 s30, s30, s76
	v_add_u32_e32 v1, s30, v0
	v_lshrrev_b32_e32 v4, 5, v1
	v_mul_u32_u24_e32 v4, 0xba2f, v4
	v_lshrrev_b32_e32 v2, 19, v4
	v_mul_u32_u24_e32 v4, 0x160, v2
	v_sub_u32_e32 v3, v1, v4
	v_and_b32_e32 v5, 1, v2
	v_lshrrev_b32_e32 v6, 1, v2
	v_lshlrev_b32_e32 v12, 6, v1
	v_and_b32_e32 v7, 31, v6
	v_mul_u32_u24_e32 v4, 31, v5
	v_cmp_ne_u32_e32 vcc, v7, v4
	v_lshlrev_b32_e32 v4, 1, v5
	v_subrev_u32_e32 v4, 1, v4
	v_mul_i32_i24_e32 v4, 0x5800, v4
	v_add_u32_e32 v13, v12, v4
	v_cndmask_b32_e32 v13, v12, v13, vcc
	v_cndmask_b32_e64 v26, 0, 1.0, vcc
	v_cndmask_b32_e64 v27, 0, 1.0, vcc
	v_mul_u32_u24_e32 v14, 0xb000, v5
	v_lshl_add_u32 v14, v3, 5, v14
	v_lshlrev_b32_e32 v4, 6, v6
	v_mad_u32_u24 v4, v5, 63, v4
	v_mul_lo_u32 v4, v4, s78
	v_lshl_add_u32 v24, v3, 4, v4
	global_load_dwordx4 v[96:99], v12, s[68:69] offset:32
	global_load_dwordx4 v[100:103], v12, s[68:69] offset:48
	global_load_dwordx4 v[104:107], v13, s[68:69]
	global_load_dwordx4 v[108:111], v13, s[68:69] offset:16
	global_load_dwordx4 v[112:115], v14, s[10:11]
	global_load_dwordx4 v[116:119], v14, s[10:11] offset:16
	global_load_dwordx4 v[120:123], v14, s[72:73]
	global_load_dwordx4 v[124:127], v14, s[72:73] offset:16
	s_add_i32 s30, s30, s76
	s_waitcnt vmcnt(0)
	v_lshlrev_b32_e32 v128, 16, v40
	v_and_b32_e32 v129, s55, v40
	v_lshlrev_b32_e32 v130, 16, v41
	v_and_b32_e32 v131, s55, v41
	v_lshlrev_b32_e32 v132, 16, v42
	v_and_b32_e32 v133, s55, v42
	v_lshlrev_b32_e32 v134, 16, v43
	v_and_b32_e32 v135, s55, v43
	v_lshlrev_b32_e32 v136, 16, v44
	v_and_b32_e32 v137, s55, v44
	v_lshlrev_b32_e32 v138, 16, v45
	v_and_b32_e32 v139, s55, v45
	v_lshlrev_b32_e32 v140, 16, v46
	v_and_b32_e32 v141, s55, v46
	v_lshlrev_b32_e32 v142, 16, v47
	v_and_b32_e32 v143, s55, v47
	v_pk_mul_f32 v[128:129], v[128:129], v[18:19]
	v_pk_mul_f32 v[130:131], v[130:131], v[18:19]
	v_pk_mul_f32 v[132:133], v[132:133], v[18:19]
	v_pk_mul_f32 v[134:135], v[134:135], v[18:19]
	v_pk_mul_f32 v[136:137], v[136:137], v[18:19]
	v_pk_mul_f32 v[138:139], v[138:139], v[18:19]
	v_pk_mul_f32 v[140:141], v[140:141], v[18:19]
	v_pk_mul_f32 v[142:143], v[142:143], v[18:19]
	v_lshlrev_b32_e32 v144, 16, v32
	v_and_b32_e32 v145, s55, v32
	v_lshlrev_b32_e32 v146, 16, v33
	v_and_b32_e32 v147, s55, v33
	v_lshlrev_b32_e32 v148, 16, v34
	v_and_b32_e32 v149, s55, v34
	v_lshlrev_b32_e32 v150, 16, v35
	v_and_b32_e32 v151, s55, v35
	v_lshlrev_b32_e32 v152, 16, v36
	v_and_b32_e32 v153, s55, v36
	v_lshlrev_b32_e32 v154, 16, v37
	v_and_b32_e32 v155, s55, v37
	v_lshlrev_b32_e32 v156, 16, v38
	v_and_b32_e32 v157, s55, v38
	v_lshlrev_b32_e32 v158, 16, v39
	v_and_b32_e32 v159, s55, v39
	v_pk_fma_f32 v[144:145], v[48:49], v[128:129], v[144:145]
	v_pk_fma_f32 v[146:147], v[50:51], v[130:131], v[146:147]
	v_pk_fma_f32 v[148:149], v[52:53], v[132:133], v[148:149]
	v_pk_fma_f32 v[150:151], v[54:55], v[134:135], v[150:151]
	v_pk_fma_f32 v[152:153], v[56:57], v[136:137], v[152:153]
	v_pk_fma_f32 v[154:155], v[58:59], v[138:139], v[154:155]
	v_pk_fma_f32 v[156:157], v[60:61], v[140:141], v[156:157]
	v_pk_fma_f32 v[158:159], v[62:63], v[142:143], v[158:159]
	v_pk_mul_f32 v[128:129], v[144:145], v[144:145]
	v_pk_mul_f32 v[130:131], v[146:147], v[146:147]
	v_pk_mul_f32 v[132:133], v[148:149], v[148:149]
	v_pk_mul_f32 v[134:135], v[150:151], v[150:151]
	v_pk_fma_f32 v[128:129], v[128:129], v[8:9], v[10:11]
	v_pk_fma_f32 v[130:131], v[130:131], v[8:9], v[10:11]
	v_pk_fma_f32 v[132:133], v[132:133], v[8:9], v[10:11]
	v_pk_fma_f32 v[134:135], v[134:135], v[8:9], v[10:11]
	v_pk_mul_f32 v[128:129], v[144:145], v[128:129]
	v_pk_mul_f32 v[130:131], v[146:147], v[130:131]
	v_pk_mul_f32 v[132:133], v[148:149], v[132:133]
	v_pk_mul_f32 v[134:135], v[150:151], v[134:135]
	v_exp_f32_e32 v128, v128
	v_exp_f32_e32 v129, v129
	v_exp_f32_e32 v130, v130
	v_exp_f32_e32 v131, v131
	v_exp_f32_e32 v132, v132
	v_exp_f32_e32 v133, v133
	v_exp_f32_e32 v134, v134
	v_exp_f32_e32 v135, v135
	s_nop 0
	v_pk_add_f32 v[128:129], v[128:129], 1.0 op_sel_hi:[1,0]
	v_pk_add_f32 v[130:131], v[130:131], 1.0 op_sel_hi:[1,0]
	v_pk_add_f32 v[132:133], v[132:133], 1.0 op_sel_hi:[1,0]
	v_pk_add_f32 v[134:135], v[134:135], 1.0 op_sel_hi:[1,0]
	v_rcp_f32_e32 v128, v128
	v_rcp_f32_e32 v129, v129
	v_rcp_f32_e32 v130, v130
	v_rcp_f32_e32 v131, v131
	v_rcp_f32_e32 v132, v132
	v_rcp_f32_e32 v133, v133
	v_rcp_f32_e32 v134, v134
	v_rcp_f32_e32 v135, v135
	s_nop 0
	v_pk_mul_f32 v[144:145], v[144:145], v[128:129]
	v_pk_mul_f32 v[146:147], v[146:147], v[130:131]
	v_pk_mul_f32 v[148:149], v[148:149], v[132:133]
	v_pk_mul_f32 v[150:151], v[150:151], v[134:135]
	v_pk_mul_f32 v[144:145], v[144:145], v[152:153]
	v_pk_mul_f32 v[146:147], v[146:147], v[154:155]
	v_pk_mul_f32 v[148:149], v[148:149], v[156:157]
	v_pk_mul_f32 v[150:151], v[150:151], v[158:159]
	v_cvt_pk_bf16_f32 v136, v144, v145
; __device__ __forceinline__ float gelu_tanh(float x) { const float z = x * ((x * x) * (-0.10294324f) + (-2.3022082f)); return x * __builtin_amdgcn_rcpf(1.f + __builtin_amdgcn_exp2f(z)); }
; __device__ void phase_ffn_fix(PP P, int wid, int layer) {
;     ...
;     for (int it = blockIdx.x * NTHREADS + tidx; it < NQ * 2 * 352; it += gridDim.x * NTHREADS) {
;         const int c8 = (it % 352) * 8, qs = it / 352, q = qs >> 1, sd = qs & 1;
;         const int row = q * 64 + (sd ? 63 : 0), l = row & (SEQL - 1);
;         const int cg = c8 >> 3;
;         const bf16_t* me = eb + ((size_t)((q * 2 + sd) * 352 + cg) * 4) * 8;
;         float pa[8], pv[8];
;         unpack8(*(const u32x4*)(me + 16), pa); unpack8(*(const u32x4*)(me + 24), pv);
;         const bool has_nb = sd ? (l < SEQL - 1) : (l > 0);
;         if (has_nb) {
;             const bf16_t* nb = eb + ((size_t)(((sd ? q + 1 : q - 1) * 2 + (sd ? 0 : 1)) * 352 + cg) * 4) * 8;
;             float ra[8], rv[8], wa[8], wv[8];
;             unpack8(*(const u32x4*)(nb), ra); unpack8(*(const u32x4*)(nb + 8), rv);
;             load8f(cw + (sd ? 2 : 0) * F2 + c8, wa); load8f(cw + (sd ? 2 : 0) * F2 + F + c8, wv);
; #pragma unroll
;             for (int e = 0; e < 8; ++e) { pa[e] += wa[e] * ra[e]; pv[e] += wv[e] * rv[e]; }
;         }
;         float o[8];
; #pragma unroll
;         for (int e = 0; e < 8; ++e) o[e] = gelu_tanh(pa[e]) * pv[e];
;         *(u32x4*)(G + (size_t)row * F + c8) = pack8(o);
;     }
	v_cvt_pk_bf16_f32 v137, v146, v147
	v_cvt_pk_bf16_f32 v138, v148, v149
	v_cvt_pk_bf16_f32 v139, v150, v151
	global_store_dwordx4 v16, v[136:139], s[56:57]
	v_lshlrev_b32_e32 v128, 16, v72
	v_and_b32_e32 v129, s55, v72
	v_lshlrev_b32_e32 v130, 16, v73
	v_and_b32_e32 v131, s55, v73
	v_lshlrev_b32_e32 v132, 16, v74
	v_and_b32_e32 v133, s55, v74
	v_lshlrev_b32_e32 v134, 16, v75
	v_and_b32_e32 v135, s55, v75
	v_lshlrev_b32_e32 v136, 16, v76
	v_and_b32_e32 v137, s55, v76
	v_lshlrev_b32_e32 v138, 16, v77
	v_and_b32_e32 v139, s55, v77
	v_lshlrev_b32_e32 v140, 16, v78
	v_and_b32_e32 v141, s55, v78
	v_lshlrev_b32_e32 v142, 16, v79
	v_and_b32_e32 v143, s55, v79
	v_pk_mul_f32 v[128:129], v[128:129], v[22:23]
	v_pk_mul_f32 v[130:131], v[130:131], v[22:23]
	v_pk_mul_f32 v[132:133], v[132:133], v[22:23]
	v_pk_mul_f32 v[134:135], v[134:135], v[22:23]
	v_pk_mul_f32 v[136:137], v[136:137], v[22:23]
	v_pk_mul_f32 v[138:139], v[138:139], v[22:23]
	v_pk_mul_f32 v[140:141], v[140:141], v[22:23]
	v_pk_mul_f32 v[142:143], v[142:143], v[22:23]
	v_lshlrev_b32_e32 v144, 16, v64
	v_and_b32_e32 v145, s55, v64
	v_lshlrev_b32_e32 v146, 16, v65
	v_and_b32_e32 v147, s55, v65
	v_lshlrev_b32_e32 v148, 16, v66
	v_and_b32_e32 v149, s55, v66
	v_lshlrev_b32_e32 v150, 16, v67
	v_and_b32_e32 v151, s55, v67
	v_lshlrev_b32_e32 v152, 16, v68
	v_and_b32_e32 v153, s55, v68
	v_lshlrev_b32_e32 v154, 16, v69
	v_and_b32_e32 v155, s55, v69
	v_lshlrev_b32_e32 v156, 16, v70
	v_and_b32_e32 v157, s55, v70
	v_lshlrev_b32_e32 v158, 16, v71
	v_and_b32_e32 v159, s55, v71
	v_pk_fma_f32 v[144:145], v[80:81], v[128:129], v[144:145]
	v_pk_fma_f32 v[146:147], v[82:83], v[130:131], v[146:147]
	v_pk_fma_f32 v[148:149], v[84:85], v[132:133], v[148:149]
	v_pk_fma_f32 v[150:151], v[86:87], v[134:135], v[150:151]
	v_pk_fma_f32 v[152:153], v[88:89], v[136:137], v[152:153]
	v_pk_fma_f32 v[154:155], v[90:91], v[138:139], v[154:155]
	v_pk_fma_f32 v[156:157], v[92:93], v[140:141], v[156:157]
	v_pk_fma_f32 v[158:159], v[94:95], v[142:143], v[158:159]
	v_pk_mul_f32 v[128:129], v[144:145], v[144:145]
	v_pk_mul_f32 v[130:131], v[146:147], v[146:147]
	v_pk_mul_f32 v[132:133], v[148:149], v[148:149]
	v_pk_mul_f32 v[134:135], v[150:151], v[150:151]
	v_pk_fma_f32 v[128:129], v[128:129], v[8:9], v[10:11]
	v_pk_fma_f32 v[130:131], v[130:131], v[8:9], v[10:11]
	v_pk_fma_f32 v[132:133], v[132:133], v[8:9], v[10:11]
	v_pk_fma_f32 v[134:135], v[134:135], v[8:9], v[10:11]
	v_pk_mul_f32 v[128:129], v[144:145], v[128:129]
	v_pk_mul_f32 v[130:131], v[146:147], v[130:131]
	v_pk_mul_f32 v[132:133], v[148:149], v[132:133]
	v_pk_mul_f32 v[134:135], v[150:151], v[134:135]
	v_exp_f32_e32 v128, v128
	v_exp_f32_e32 v129, v129
	v_exp_f32_e32 v130, v130
	v_exp_f32_e32 v131, v131
	v_exp_f32_e32 v132, v132
	v_exp_f32_e32 v133, v133
	v_exp_f32_e32 v134, v134
	v_exp_f32_e32 v135, v135
	s_nop 0
	v_pk_add_f32 v[128:129], v[128:129], 1.0 op_sel_hi:[1,0]
	v_pk_add_f32 v[130:131], v[130:131], 1.0 op_sel_hi:[1,0]
	v_pk_add_f32 v[132:133], v[132:133], 1.0 op_sel_hi:[1,0]
	v_pk_add_f32 v[134:135], v[134:135], 1.0 op_sel_hi:[1,0]
	v_rcp_f32_e32 v128, v128
	v_rcp_f32_e32 v129, v129
	v_rcp_f32_e32 v130, v130
	v_rcp_f32_e32 v131, v131
	v_rcp_f32_e32 v132, v132
	v_rcp_f32_e32 v133, v133
	v_rcp_f32_e32 v134, v134
	v_rcp_f32_e32 v135, v135
	s_nop 0
	v_pk_mul_f32 v[144:145], v[144:145], v[128:129]
	v_pk_mul_f32 v[146:147], v[146:147], v[130:131]
	v_pk_mul_f32 v[148:149], v[148:149], v[132:133]
	v_pk_mul_f32 v[150:151], v[150:151], v[134:135]
	v_pk_mul_f32 v[144:145], v[144:145], v[152:153]
	v_pk_mul_f32 v[146:147], v[146:147], v[154:155]
	v_pk_mul_f32 v[148:149], v[148:149], v[156:157]
	v_pk_mul_f32 v[150:151], v[150:151], v[158:159]
	v_cvt_pk_bf16_f32 v136, v144, v145
	v_cvt_pk_bf16_f32 v137, v146, v147
	v_cvt_pk_bf16_f32 v138, v148, v149
	v_cvt_pk_bf16_f32 v139, v150, v151
	global_store_dwordx4 v20, v[136:139], s[56:57]
	v_lshlrev_b32_e32 v128, 16, v104
	v_and_b32_e32 v129, s55, v104
	v_lshlrev_b32_e32 v130, 16, v105
	v_and_b32_e32 v131, s55, v105
	v_lshlrev_b32_e32 v132, 16, v106
	v_and_b32_e32 v133, s55, v106
	v_lshlrev_b32_e32 v134, 16, v107
	v_and_b32_e32 v135, s55, v107
	v_lshlrev_b32_e32 v136, 16, v108
	v_and_b32_e32 v137, s55, v108
	v_lshlrev_b32_e32 v138, 16, v109
	v_and_b32_e32 v139, s55, v109
	v_lshlrev_b32_e32 v140, 16, v110
	v_and_b32_e32 v141, s55, v110
	v_lshlrev_b32_e32 v142, 16, v111
	v_and_b32_e32 v143, s55, v111
	v_pk_mul_f32 v[128:129], v[128:129], v[26:27]
	v_pk_mul_f32 v[130:131], v[130:131], v[26:27]
	v_pk_mul_f32 v[132:133], v[132:133], v[26:27]
	v_pk_mul_f32 v[134:135], v[134:135], v[26:27]
	v_pk_mul_f32 v[136:137], v[136:137], v[26:27]
	v_pk_mul_f32 v[138:139], v[138:139], v[26:27]
	v_pk_mul_f32 v[140:141], v[140:141], v[26:27]
	v_pk_mul_f32 v[142:143], v[142:143], v[26:27]
	v_lshlrev_b32_e32 v144, 16, v96
	v_and_b32_e32 v145, s55, v96
	v_lshlrev_b32_e32 v146, 16, v97
	v_and_b32_e32 v147, s55, v97
	v_lshlrev_b32_e32 v148, 16, v98
	v_and_b32_e32 v149, s55, v98
	v_lshlrev_b32_e32 v150, 16, v99
	v_and_b32_e32 v151, s55, v99
	v_lshlrev_b32_e32 v152, 16, v100
	v_and_b32_e32 v153, s55, v100
	v_lshlrev_b32_e32 v154, 16, v101
	v_and_b32_e32 v155, s55, v101
	v_lshlrev_b32_e32 v156, 16, v102
	v_and_b32_e32 v157, s55, v102
	v_lshlrev_b32_e32 v158, 16, v103
	v_and_b32_e32 v159, s55, v103
	v_pk_fma_f32 v[144:145], v[112:113], v[128:129], v[144:145]
	v_pk_fma_f32 v[146:147], v[114:115], v[130:131], v[146:147]
	v_pk_fma_f32 v[148:149], v[116:117], v[132:133], v[148:149]
	v_pk_fma_f32 v[150:151], v[118:119], v[134:135], v[150:151]
	v_pk_fma_f32 v[152:153], v[120:121], v[136:137], v[152:153]
	v_pk_fma_f32 v[154:155], v[122:123], v[138:139], v[154:155]
; __device__ __forceinline__ float gelu_tanh(float x) { const float z = x * ((x * x) * (-0.10294324f) + (-2.3022082f)); return x * __builtin_amdgcn_rcpf(1.f + __builtin_amdgcn_exp2f(z)); }
; __device__ void phase_ffn_fix(PP P, int wid, int layer) {
;     ...
;     for (int it = blockIdx.x * NTHREADS + tidx; it < NQ * 2 * 352; it += gridDim.x * NTHREADS) {
;         const int c8 = (it % 352) * 8, qs = it / 352, q = qs >> 1, sd = qs & 1;
;         const int row = q * 64 + (sd ? 63 : 0), l = row & (SEQL - 1);
;         const int cg = c8 >> 3;
;         const bf16_t* me = eb + ((size_t)((q * 2 + sd) * 352 + cg) * 4) * 8;
;         float pa[8], pv[8];
;         unpack8(*(const u32x4*)(me + 16), pa); unpack8(*(const u32x4*)(me + 24), pv);
;         const bool has_nb = sd ? (l < SEQL - 1) : (l > 0);
;         if (has_nb) {
;             const bf16_t* nb = eb + ((size_t)(((sd ? q + 1 : q - 1) * 2 + (sd ? 0 : 1)) * 352 + cg) * 4) * 8;
;             float ra[8], rv[8], wa[8], wv[8];
;             unpack8(*(const u32x4*)(nb), ra); unpack8(*(const u32x4*)(nb + 8), rv);
;             load8f(cw + (sd ? 2 : 0) * F2 + c8, wa); load8f(cw + (sd ? 2 : 0) * F2 + F + c8, wv);
; #pragma unroll
;             for (int e = 0; e < 8; ++e) { pa[e] += wa[e] * ra[e]; pv[e] += wv[e] * rv[e]; }
;         }
;         float o[8];
; #pragma unroll
;         for (int e = 0; e < 8; ++e) o[e] = gelu_tanh(pa[e]) * pv[e];
;         *(u32x4*)(G + (size_t)row * F + c8) = pack8(o);
;     }
	v_pk_fma_f32 v[156:157], v[124:125], v[140:141], v[156:157]
	v_pk_fma_f32 v[158:159], v[126:127], v[142:143], v[158:159]
	v_pk_mul_f32 v[128:129], v[144:145], v[144:145]
	v_pk_mul_f32 v[130:131], v[146:147], v[146:147]
	v_pk_mul_f32 v[132:133], v[148:149], v[148:149]
	v_pk_mul_f32 v[134:135], v[150:151], v[150:151]
	v_pk_fma_f32 v[128:129], v[128:129], v[8:9], v[10:11]
	v_pk_fma_f32 v[130:131], v[130:131], v[8:9], v[10:11]
	v_pk_fma_f32 v[132:133], v[132:133], v[8:9], v[10:11]
	v_pk_fma_f32 v[134:135], v[134:135], v[8:9], v[10:11]
	v_pk_mul_f32 v[128:129], v[144:145], v[128:129]
	v_pk_mul_f32 v[130:131], v[146:147], v[130:131]
	v_pk_mul_f32 v[132:133], v[148:149], v[132:133]
	v_pk_mul_f32 v[134:135], v[150:151], v[134:135]
	v_exp_f32_e32 v128, v128
	v_exp_f32_e32 v129, v129
	v_exp_f32_e32 v130, v130
	v_exp_f32_e32 v131, v131
	v_exp_f32_e32 v132, v132
	v_exp_f32_e32 v133, v133
	v_exp_f32_e32 v134, v134
	v_exp_f32_e32 v135, v135
	s_nop 0
	v_pk_add_f32 v[128:129], v[128:129], 1.0 op_sel_hi:[1,0]
	v_pk_add_f32 v[130:131], v[130:131], 1.0 op_sel_hi:[1,0]
	v_pk_add_f32 v[132:133], v[132:133], 1.0 op_sel_hi:[1,0]
	v_pk_add_f32 v[134:135], v[134:135], 1.0 op_sel_hi:[1,0]
	v_rcp_f32_e32 v128, v128
	v_rcp_f32_e32 v129, v129
	v_rcp_f32_e32 v130, v130
	v_rcp_f32_e32 v131, v131
	v_rcp_f32_e32 v132, v132
	v_rcp_f32_e32 v133, v133
	v_rcp_f32_e32 v134, v134
	v_rcp_f32_e32 v135, v135
	s_nop 0
	v_pk_mul_f32 v[144:145], v[144:145], v[128:129]
	v_pk_mul_f32 v[146:147], v[146:147], v[130:131]
	v_pk_mul_f32 v[148:149], v[148:149], v[132:133]
	v_pk_mul_f32 v[150:151], v[150:151], v[134:135]
	v_pk_mul_f32 v[144:145], v[144:145], v[152:153]
	v_pk_mul_f32 v[146:147], v[146:147], v[154:155]
	v_pk_mul_f32 v[148:149], v[148:149], v[156:157]
	v_pk_mul_f32 v[150:151], v[150:151], v[158:159]
	v_cvt_pk_bf16_f32 v136, v144, v145
	v_cvt_pk_bf16_f32 v137, v146, v147
	v_cvt_pk_bf16_f32 v138, v148, v149
	v_cvt_pk_bf16_f32 v139, v150, v151
	global_store_dwordx4 v24, v[136:139], s[56:57]
	s_cmp_lt_u32 s2, 0xe0
	s_cbranch_scc0 .Lfx_end
	v_add_u32_e32 v1, s30, v0
	v_lshrrev_b32_e32 v4, 5, v1
	v_mul_u32_u24_e32 v4, 0xba2f, v4
	v_lshrrev_b32_e32 v2, 19, v4
	v_mul_u32_u24_e32 v4, 0x160, v2
	v_sub_u32_e32 v3, v1, v4
	v_and_b32_e32 v5, 1, v2
	v_lshrrev_b32_e32 v6, 1, v2
	v_lshlrev_b32_e32 v12, 6, v1
	v_and_b32_e32 v7, 31, v6
	v_mul_u32_u24_e32 v4, 31, v5
	v_cmp_ne_u32_e32 vcc, v7, v4
	v_lshlrev_b32_e32 v4, 1, v5
	v_subrev_u32_e32 v4, 1, v4
	v_mul_i32_i24_e32 v4, 0x5800, v4
	v_add_u32_e32 v13, v12, v4
	v_cndmask_b32_e32 v13, v12, v13, vcc
	v_cndmask_b32_e64 v18, 0, 1.0, vcc
	v_cndmask_b32_e64 v19, 0, 1.0, vcc
	v_mul_u32_u24_e32 v14, 0xb000, v5
	v_lshl_add_u32 v14, v3, 5, v14
	v_lshlrev_b32_e32 v4, 6, v6
	v_mad_u32_u24 v4, v5, 63, v4
	v_mul_lo_u32 v4, v4, s78
	v_lshl_add_u32 v16, v3, 4, v4
	global_load_dwordx4 v[32:35], v12, s[68:69] offset:32
	global_load_dwordx4 v[36:39], v12, s[68:69] offset:48
	global_load_dwordx4 v[40:43], v13, s[68:69]
	global_load_dwordx4 v[44:47], v13, s[68:69] offset:16
	global_load_dwordx4 v[48:51], v14, s[10:11]
	global_load_dwordx4 v[52:55], v14, s[10:11] offset:16
	global_load_dwordx4 v[56:59], v14, s[72:73]
	global_load_dwordx4 v[60:63], v14, s[72:73] offset:16
	s_add_i32 s30, s30, s76
	s_waitcnt vmcnt(0)
	v_lshlrev_b32_e32 v128, 16, v40
	v_and_b32_e32 v129, s55, v40
	v_lshlrev_b32_e32 v130, 16, v41
	v_and_b32_e32 v131, s55, v41
	v_lshlrev_b32_e32 v132, 16, v42
	v_and_b32_e32 v133, s55, v42
	v_lshlrev_b32_e32 v134, 16, v43
	v_and_b32_e32 v135, s55, v43
	v_lshlrev_b32_e32 v136, 16, v44
	v_and_b32_e32 v137, s55, v44
	v_lshlrev_b32_e32 v138, 16, v45
	v_and_b32_e32 v139, s55, v45
	v_lshlrev_b32_e32 v140, 16, v46
	v_and_b32_e32 v141, s55, v46
	v_lshlrev_b32_e32 v142, 16, v47
	v_and_b32_e32 v143, s55, v47
	v_pk_mul_f32 v[128:129], v[128:129], v[18:19]
	v_pk_mul_f32 v[130:131], v[130:131], v[18:19]
	v_pk_mul_f32 v[132:133], v[132:133], v[18:19]
	v_pk_mul_f32 v[134:135], v[134:135], v[18:19]
	v_pk_mul_f32 v[136:137], v[136:137], v[18:19]
	v_pk_mul_f32 v[138:139], v[138:139], v[18:19]
	v_pk_mul_f32 v[140:141], v[140:141], v[18:19]
	v_pk_mul_f32 v[142:143], v[142:143], v[18:19]
	v_lshlrev_b32_e32 v144, 16, v32
	v_and_b32_e32 v145, s55, v32
	v_lshlrev_b32_e32 v146, 16, v33
	v_and_b32_e32 v147, s55, v33
	v_lshlrev_b32_e32 v148, 16, v34
	v_and_b32_e32 v149, s55, v34
	v_lshlrev_b32_e32 v150, 16, v35
	v_and_b32_e32 v151, s55, v35
	v_lshlrev_b32_e32 v152, 16, v36
	v_and_b32_e32 v153, s55, v36
	v_lshlrev_b32_e32 v154, 16, v37
	v_and_b32_e32 v155, s55, v37
	v_lshlrev_b32_e32 v156, 16, v38
	v_and_b32_e32 v157, s55, v38
	v_lshlrev_b32_e32 v158, 16, v39
	v_and_b32_e32 v159, s55, v39
	v_pk_fma_f32 v[144:145], v[48:49], v[128:129], v[144:145]
	v_pk_fma_f32 v[146:147], v[50:51], v[130:131], v[146:147]
	v_pk_fma_f32 v[148:149], v[52:53], v[132:133], v[148:149]
	v_pk_fma_f32 v[150:151], v[54:55], v[134:135], v[150:151]
	v_pk_fma_f32 v[152:153], v[56:57], v[136:137], v[152:153]
	v_pk_fma_f32 v[154:155], v[58:59], v[138:139], v[154:155]
	v_pk_fma_f32 v[156:157], v[60:61], v[140:141], v[156:157]
	v_pk_fma_f32 v[158:159], v[62:63], v[142:143], v[158:159]
	v_pk_mul_f32 v[128:129], v[144:145], v[144:145]
	v_pk_mul_f32 v[130:131], v[146:147], v[146:147]
	v_pk_mul_f32 v[132:133], v[148:149], v[148:149]
	v_pk_mul_f32 v[134:135], v[150:151], v[150:151]
	v_pk_fma_f32 v[128:129], v[128:129], v[8:9], v[10:11]
	v_pk_fma_f32 v[130:131], v[130:131], v[8:9], v[10:11]
	v_pk_fma_f32 v[132:133], v[132:133], v[8:9], v[10:11]
	v_pk_fma_f32 v[134:135], v[134:135], v[8:9], v[10:11]
	v_pk_mul_f32 v[128:129], v[144:145], v[128:129]
	v_pk_mul_f32 v[130:131], v[146:147], v[130:131]
	v_pk_mul_f32 v[132:133], v[148:149], v[132:133]
	v_pk_mul_f32 v[134:135], v[150:151], v[134:135]
	v_exp_f32_e32 v128, v128
	v_exp_f32_e32 v129, v129
	v_exp_f32_e32 v130, v130
	v_exp_f32_e32 v131, v131
	v_exp_f32_e32 v132, v132
	v_exp_f32_e32 v133, v133
	v_exp_f32_e32 v134, v134
	v_exp_f32_e32 v135, v135
	s_nop 0
	v_pk_add_f32 v[128:129], v[128:129], 1.0 op_sel_hi:[1,0]
	v_pk_add_f32 v[130:131], v[130:131], 1.0 op_sel_hi:[1,0]
	v_pk_add_f32 v[132:133], v[132:133], 1.0 op_sel_hi:[1,0]
	v_pk_add_f32 v[134:135], v[134:135], 1.0 op_sel_hi:[1,0]
	v_rcp_f32_e32 v128, v128
	v_rcp_f32_e32 v129, v129
	v_rcp_f32_e32 v130, v130
	v_rcp_f32_e32 v131, v131
	v_rcp_f32_e32 v132, v132
	v_rcp_f32_e32 v133, v133
	v_rcp_f32_e32 v134, v134
	v_rcp_f32_e32 v135, v135
	s_nop 0
	v_pk_mul_f32 v[144:145], v[144:145], v[128:129]
	v_pk_mul_f32 v[146:147], v[146:147], v[130:131]
	v_pk_mul_f32 v[148:149], v[148:149], v[132:133]
	v_pk_mul_f32 v[150:151], v[150:151], v[134:135]
	v_pk_mul_f32 v[144:145], v[144:145], v[152:153]
	v_pk_mul_f32 v[146:147], v[146:147], v[154:155]
	v_pk_mul_f32 v[148:149], v[148:149], v[156:157]
	v_pk_mul_f32 v[150:151], v[150:151], v[158:159]
	v_cvt_pk_bf16_f32 v136, v144, v145
	v_cvt_pk_bf16_f32 v137, v146, v147
	v_cvt_pk_bf16_f32 v138, v148, v149
	v_cvt_pk_bf16_f32 v139, v150, v151
	global_store_dwordx4 v16, v[136:139], s[56:57]
.Lfx_end:
	s_mov_b64 s[8:9], exec
